# v23: v22 + prologue adaLN GEMV: the next 7 weight rows of each 8-row group are touched up front so the serialized per-row loads hit cache
# speedup vs baseline: 1.0066x; 1.0035x over previous
; __device__ __forceinline__ void prologue(const Params& p, LAS unsigned char* lds, int tid, int wave, int lane, int G) {
;     ...
;         for (int unit = blockIdx.x; unit < DEPTH * 144; unit += G) {
;             const int l = unit / 144, n0 = (unit % 144) * 64;
;             const float* Wp = p.ada_w + (size_t)l * DM * (NMOD * DM) + n0 + 4 * c4;
;             f32x4 acc[8];
; #pragma unroll
;             for (int r = 0; r < 8; ++r) acc[r] = (f32x4){0.f, 0.f, 0.f, 0.f};
; #pragma unroll 8
;             for (int k = k32 * 32; k < k32 * 32 + 32; ++k) { const f32x4 w = *(const f32x4*)(Wp + (size_t)k * (NMOD * DM));
; #pragma unroll
;                 for (int r = 0; r < 8; ++r) acc[r] += w * cond[r * DM + k]; }
.LBB0_811:
	v_lshl_add_u64 v[46:47], v[44:45], 0, s[12:13]
	global_load_dwordx4 v[48:51], v[46:47], off
	s_mov_b64 vcc, 0x9000
	v_mov_b64_e32 v[100:101], v[46:47]
	v_lshl_add_u64 v[100:101], v[100:101], 0, vcc
	global_load_dwordx4 v[104:107], v[100:101], off
	v_lshl_add_u64 v[100:101], v[100:101], 0, vcc
	global_load_dwordx4 v[104:107], v[100:101], off
	v_lshl_add_u64 v[100:101], v[100:101], 0, vcc
	global_load_dwordx4 v[104:107], v[100:101], off
	v_lshl_add_u64 v[100:101], v[100:101], 0, vcc
	global_load_dwordx4 v[104:107], v[100:101], off
	v_lshl_add_u64 v[100:101], v[100:101], 0, vcc
	global_load_dwordx4 v[104:107], v[100:101], off
	v_lshl_add_u64 v[100:101], v[100:101], 0, vcc
	global_load_dwordx4 v[104:107], v[100:101], off
	v_lshl_add_u64 v[100:101], v[100:101], 0, vcc
	global_load_dwordx4 v[104:107], v[100:101], off
	ds_read_b128 v[56:59], v55
	ds_read_b128 v[34:37], v55 offset:16
	s_mov_b32 s2, 0x1b000
	s_add_u32 s12, s12, 0x48000
	s_addc_u32 s13, s13, 0
	s_cmp_eq_u32 s12, 0x120000
	ds_read_b128 v[60:63], v55 offset:20480
	ds_read_b128 v[64:67], v55 offset:24576
	ds_read_b128 v[68:71], v55 offset:28672
	s_waitcnt vmcnt(0) lgkmcnt(4)
	v_pk_fma_f32 v[72:73], v[50:51], v[56:57], v[6:7] op_sel_hi:[1,0,1]
	v_pk_fma_f32 v[74:75], v[48:49], v[56:57], v[4:5] op_sel_hi:[1,0,1]
	ds_read_b128 v[4:7], v55 offset:4096
	s_waitcnt lgkmcnt(3)
	v_pk_fma_f32 v[26:27], v[48:49], v[60:61], v[26:27] op_sel_hi:[1,0,1]
	s_waitcnt lgkmcnt(2)
	v_pk_fma_f32 v[30:31], v[48:49], v[64:65], v[30:31] op_sel_hi:[1,0,1]
	v_pk_fma_f32 v[28:29], v[50:51], v[60:61], v[28:29] op_sel_hi:[1,0,1]
	v_pk_fma_f32 v[32:33], v[50:51], v[64:65], v[32:33] op_sel_hi:[1,0,1]
	s_waitcnt lgkmcnt(0)
	v_pk_fma_f32 v[76:77], v[50:51], v[4:5], v[10:11] op_sel_hi:[1,0,1]
	v_pk_fma_f32 v[78:79], v[48:49], v[4:5], v[8:9] op_sel_hi:[1,0,1]
	ds_read_b128 v[8:11], v55 offset:8192
	s_waitcnt lgkmcnt(0)
	v_pk_fma_f32 v[80:81], v[50:51], v[8:9], v[14:15] op_sel_hi:[1,0,1]
	v_pk_fma_f32 v[82:83], v[48:49], v[8:9], v[12:13] op_sel_hi:[1,0,1]
	ds_read_b128 v[12:15], v55 offset:12288
	s_waitcnt lgkmcnt(0)
	v_pk_fma_f32 v[84:85], v[50:51], v[12:13], v[20:21] op_sel_hi:[1,0,1]
	v_pk_fma_f32 v[86:87], v[48:49], v[12:13], v[18:19] op_sel_hi:[1,0,1]
	ds_read_b128 v[18:21], v55 offset:16384
	s_waitcnt lgkmcnt(0)
	v_pk_fma_f32 v[22:23], v[48:49], v[18:19], v[22:23] op_sel_hi:[1,0,1]
	v_pk_fma_f32 v[48:49], v[48:49], v[68:69], v[0:1] op_sel_hi:[1,0,1]
	v_add_co_u32_e32 v0, vcc, s97, v46
	v_pk_fma_f32 v[24:25], v[50:51], v[18:19], v[24:25] op_sel_hi:[1,0,1]
	s_nop 0
	v_addc_co_u32_e32 v1, vcc, 0, v47, vcc
	v_pk_fma_f32 v[50:51], v[50:51], v[68:69], v[2:3] op_sel_hi:[1,0,1]
	global_load_dwordx4 v[0:3], v[0:1], off
	s_waitcnt vmcnt(0)
	v_pk_fma_f32 v[74:75], v[0:1], v[56:57], v[74:75] op_sel:[0,1,0]
	v_pk_fma_f32 v[56:57], v[2:3], v[56:57], v[72:73] op_sel:[0,1,0]
	v_pk_fma_f32 v[72:73], v[0:1], v[4:5], v[78:79] op_sel:[0,1,0]
	v_pk_fma_f32 v[4:5], v[2:3], v[4:5], v[76:77] op_sel:[0,1,0]
	v_pk_fma_f32 v[76:77], v[0:1], v[8:9], v[82:83] op_sel:[0,1,0]
	v_pk_fma_f32 v[78:79], v[0:1], v[12:13], v[86:87] op_sel:[0,1,0]
	v_pk_fma_f32 v[22:23], v[0:1], v[18:19], v[22:23] op_sel:[0,1,0]
	v_pk_fma_f32 v[18:19], v[2:3], v[18:19], v[24:25] op_sel:[0,1,0]
	v_pk_fma_f32 v[24:25], v[0:1], v[60:61], v[26:27] op_sel:[0,1,0]
	v_pk_fma_f32 v[26:27], v[2:3], v[60:61], v[28:29] op_sel:[0,1,0]
	v_pk_fma_f32 v[28:29], v[0:1], v[64:65], v[30:31] op_sel:[0,1,0]
	v_pk_fma_f32 v[30:31], v[2:3], v[64:65], v[32:33] op_sel:[0,1,0]
	v_pk_fma_f32 v[32:33], v[0:1], v[68:69], v[48:49] op_sel:[0,1,0]
	v_add_co_u32_e32 v0, vcc, s33, v46
	v_pk_fma_f32 v[8:9], v[2:3], v[8:9], v[80:81] op_sel:[0,1,0]
	s_nop 0
	v_addc_co_u32_e32 v1, vcc, 0, v47, vcc
	v_pk_fma_f32 v[12:13], v[2:3], v[12:13], v[84:85] op_sel:[0,1,0]
	v_pk_fma_f32 v[48:49], v[2:3], v[68:69], v[50:51] op_sel:[0,1,0]
	global_load_dwordx4 v[0:3], v[0:1], off
	s_waitcnt vmcnt(0)
	v_pk_fma_f32 v[50:51], v[2:3], v[58:59], v[56:57] op_sel_hi:[1,0,1]
	v_pk_fma_f32 v[56:57], v[0:1], v[58:59], v[74:75] op_sel_hi:[1,0,1]
	v_pk_fma_f32 v[60:61], v[0:1], v[6:7], v[72:73] op_sel_hi:[1,0,1]
	v_pk_fma_f32 v[64:65], v[0:1], v[10:11], v[76:77] op_sel_hi:[1,0,1]
	v_pk_fma_f32 v[68:69], v[0:1], v[14:15], v[78:79] op_sel_hi:[1,0,1]
	v_pk_fma_f32 v[72:73], v[0:1], v[20:21], v[22:23] op_sel_hi:[1,0,1]
	v_pk_fma_f32 v[76:77], v[0:1], v[62:63], v[24:25] op_sel_hi:[1,0,1]
	v_pk_fma_f32 v[80:81], v[0:1], v[66:67], v[28:29] op_sel_hi:[1,0,1]
	v_pk_fma_f32 v[84:85], v[0:1], v[70:71], v[32:33] op_sel_hi:[1,0,1]
	v_add_co_u32_e32 v0, vcc, s2, v46
	v_pk_fma_f32 v[4:5], v[2:3], v[6:7], v[4:5] op_sel_hi:[1,0,1]
	s_nop 0
	v_addc_co_u32_e32 v1, vcc, 0, v47, vcc
	v_pk_fma_f32 v[8:9], v[2:3], v[10:11], v[8:9] op_sel_hi:[1,0,1]
	v_pk_fma_f32 v[12:13], v[2:3], v[14:15], v[12:13] op_sel_hi:[1,0,1]
	v_pk_fma_f32 v[18:19], v[2:3], v[20:21], v[18:19] op_sel_hi:[1,0,1]
	v_pk_fma_f32 v[74:75], v[2:3], v[62:63], v[26:27] op_sel_hi:[1,0,1]
	v_pk_fma_f32 v[78:79], v[2:3], v[66:67], v[30:31] op_sel_hi:[1,0,1]
	v_pk_fma_f32 v[82:83], v[2:3], v[70:71], v[48:49] op_sel_hi:[1,0,1]
	global_load_dwordx4 v[0:3], v[0:1], off
	v_mov_b32_e32 v6, v59
	s_mov_b32 s2, 0x2d000
	s_waitcnt vmcnt(0)
; __device__ __forceinline__ void prologue(const Params& p, LAS unsigned char* lds, int tid, int wave, int lane, int G) {
;     ...
; #pragma unroll 8
;             for (int k = k32 * 32; k < k32 * 32 + 32; ++k) { const f32x4 w = *(const f32x4*)(Wp + (size_t)k * (NMOD * DM));
; #pragma unroll
;                 for (int r = 0; r < 8; ++r) acc[r] += w * cond[r * DM + k]; }
	v_pk_fma_f32 v[58:59], v[2:3], v[6:7], v[50:51] op_sel_hi:[1,0,1]
	v_pk_fma_f32 v[56:57], v[0:1], v[6:7], v[56:57] op_sel_hi:[1,0,1]
	v_mov_b32_e32 v6, v7
	v_pk_fma_f32 v[48:49], v[2:3], v[6:7], v[4:5] op_sel_hi:[1,0,1]
	v_mov_b32_e32 v4, v11
	v_pk_fma_f32 v[30:31], v[2:3], v[4:5], v[8:9] op_sel_hi:[1,0,1]
	v_pk_fma_f32 v[32:33], v[0:1], v[4:5], v[64:65] op_sel_hi:[1,0,1]
	v_mov_b32_e32 v4, v15
	v_pk_fma_f32 v[26:27], v[2:3], v[4:5], v[12:13] op_sel_hi:[1,0,1]
	v_pk_fma_f32 v[28:29], v[0:1], v[4:5], v[68:69] op_sel_hi:[1,0,1]
	v_mov_b32_e32 v4, v21
	v_pk_fma_f32 v[22:23], v[2:3], v[4:5], v[18:19] op_sel_hi:[1,0,1]
	v_pk_fma_f32 v[24:25], v[0:1], v[4:5], v[72:73] op_sel_hi:[1,0,1]
	v_mov_b32_e32 v4, v63
	v_pk_fma_f32 v[18:19], v[2:3], v[4:5], v[74:75] op_sel_hi:[1,0,1]
	v_pk_fma_f32 v[20:21], v[0:1], v[4:5], v[76:77] op_sel_hi:[1,0,1]
	v_mov_b32_e32 v4, v67
	v_pk_fma_f32 v[12:13], v[2:3], v[4:5], v[78:79] op_sel_hi:[1,0,1]
	v_pk_fma_f32 v[14:15], v[0:1], v[4:5], v[80:81] op_sel_hi:[1,0,1]
	v_mov_b32_e32 v4, v71
	v_pk_fma_f32 v[50:51], v[0:1], v[6:7], v[60:61] op_sel_hi:[1,0,1]
	v_pk_fma_f32 v[10:11], v[0:1], v[4:5], v[84:85] op_sel_hi:[1,0,1]
	v_add_co_u32_e32 v0, vcc, s3, v46
	v_pk_fma_f32 v[8:9], v[2:3], v[4:5], v[82:83] op_sel_hi:[1,0,1]
	s_nop 0
	v_addc_co_u32_e32 v1, vcc, 0, v47, vcc
	global_load_dwordx4 v[0:3], v[0:1], off
	ds_read_b128 v[60:63], v55 offset:20496
	ds_read_b128 v[64:67], v55 offset:24592
	ds_read_b128 v[68:71], v55 offset:28688
	s_waitcnt vmcnt(0)
	v_pk_fma_f32 v[4:5], v[2:3], v[34:35], v[58:59] op_sel_hi:[1,0,1]
	v_pk_fma_f32 v[6:7], v[0:1], v[34:35], v[56:57] op_sel_hi:[1,0,1]
	ds_read_b128 v[56:59], v55 offset:4112
	s_waitcnt lgkmcnt(3)
	v_pk_fma_f32 v[20:21], v[0:1], v[60:61], v[20:21] op_sel_hi:[1,0,1]
	s_waitcnt lgkmcnt(2)
	v_pk_fma_f32 v[14:15], v[0:1], v[64:65], v[14:15] op_sel_hi:[1,0,1]
	s_waitcnt lgkmcnt(1)
	v_pk_fma_f32 v[10:11], v[0:1], v[68:69], v[10:11] op_sel_hi:[1,0,1]
	v_pk_fma_f32 v[18:19], v[2:3], v[60:61], v[18:19] op_sel_hi:[1,0,1]
	s_waitcnt lgkmcnt(0)
	v_pk_fma_f32 v[72:73], v[2:3], v[56:57], v[48:49] op_sel_hi:[1,0,1]
	v_pk_fma_f32 v[74:75], v[0:1], v[56:57], v[50:51] op_sel_hi:[1,0,1]
	ds_read_b128 v[48:51], v55 offset:8208
	v_pk_fma_f32 v[12:13], v[2:3], v[64:65], v[12:13] op_sel_hi:[1,0,1]
	v_pk_fma_f32 v[8:9], v[2:3], v[68:69], v[8:9] op_sel_hi:[1,0,1]
	s_waitcnt lgkmcnt(0)
	v_pk_fma_f32 v[76:77], v[2:3], v[48:49], v[30:31] op_sel_hi:[1,0,1]
	v_pk_fma_f32 v[78:79], v[0:1], v[48:49], v[32:33] op_sel_hi:[1,0,1]
	ds_read_b128 v[30:33], v55 offset:12304
	s_waitcnt lgkmcnt(0)
	v_pk_fma_f32 v[80:81], v[2:3], v[30:31], v[26:27] op_sel_hi:[1,0,1]
	v_pk_fma_f32 v[82:83], v[0:1], v[30:31], v[28:29] op_sel_hi:[1,0,1]
	ds_read_b128 v[26:29], v55 offset:16400
	v_add_u32_e32 v55, 32, v55
	s_waitcnt lgkmcnt(0)
	v_pk_fma_f32 v[24:25], v[0:1], v[26:27], v[24:25] op_sel_hi:[1,0,1]
	v_add_co_u32_e32 v0, vcc, s2, v46
	v_pk_fma_f32 v[22:23], v[2:3], v[26:27], v[22:23] op_sel_hi:[1,0,1]
	s_nop 0
	v_addc_co_u32_e32 v1, vcc, 0, v47, vcc
	global_load_dwordx4 v[0:3], v[0:1], off
	s_mov_b32 s2, 0x36000
	s_waitcnt vmcnt(0)
	v_pk_fma_f32 v[4:5], v[2:3], v[34:35], v[4:5] op_sel:[0,1,0]
	v_pk_fma_f32 v[6:7], v[0:1], v[34:35], v[6:7] op_sel:[0,1,0]
	v_pk_fma_f32 v[34:35], v[2:3], v[56:57], v[72:73] op_sel:[0,1,0]
	v_pk_fma_f32 v[56:57], v[0:1], v[56:57], v[74:75] op_sel:[0,1,0]
	v_pk_fma_f32 v[72:73], v[2:3], v[48:49], v[76:77] op_sel:[0,1,0]
	v_pk_fma_f32 v[48:49], v[0:1], v[48:49], v[78:79] op_sel:[0,1,0]
	v_pk_fma_f32 v[74:75], v[2:3], v[30:31], v[80:81] op_sel:[0,1,0]
	v_pk_fma_f32 v[30:31], v[0:1], v[30:31], v[82:83] op_sel:[0,1,0]
	v_pk_fma_f32 v[24:25], v[0:1], v[26:27], v[24:25] op_sel:[0,1,0]
	v_pk_fma_f32 v[20:21], v[0:1], v[60:61], v[20:21] op_sel:[0,1,0]
	v_pk_fma_f32 v[14:15], v[0:1], v[64:65], v[14:15] op_sel:[0,1,0]
	v_pk_fma_f32 v[10:11], v[0:1], v[68:69], v[10:11] op_sel:[0,1,0]
	v_add_co_u32_e32 v0, vcc, s2, v46
	v_pk_fma_f32 v[22:23], v[2:3], v[26:27], v[22:23] op_sel:[0,1,0]
	s_nop 0
	v_addc_co_u32_e32 v1, vcc, 0, v47, vcc
	v_pk_fma_f32 v[18:19], v[2:3], v[60:61], v[18:19] op_sel:[0,1,0]
	v_pk_fma_f32 v[12:13], v[2:3], v[64:65], v[12:13] op_sel:[0,1,0]
	v_pk_fma_f32 v[8:9], v[2:3], v[68:69], v[8:9] op_sel:[0,1,0]
	global_load_dwordx4 v[0:3], v[0:1], off
	s_mov_b32 s2, 0x3f000
	s_waitcnt vmcnt(0)
	v_pk_fma_f32 v[26:27], v[0:1], v[36:37], v[6:7] op_sel_hi:[1,0,1]
	v_pk_fma_f32 v[56:57], v[0:1], v[58:59], v[56:57] op_sel_hi:[1,0,1]
	v_pk_fma_f32 v[48:49], v[0:1], v[50:51], v[48:49] op_sel_hi:[1,0,1]
	v_pk_fma_f32 v[64:65], v[2:3], v[32:33], v[74:75] op_sel_hi:[1,0,1]
	v_pk_fma_f32 v[30:31], v[0:1], v[32:33], v[30:31] op_sel_hi:[1,0,1]
	v_pk_fma_f32 v[68:69], v[0:1], v[28:29], v[24:25] op_sel_hi:[1,0,1]
	v_pk_fma_f32 v[74:75], v[0:1], v[62:63], v[20:21] op_sel_hi:[1,0,1]
	v_pk_fma_f32 v[78:79], v[0:1], v[66:67], v[14:15] op_sel_hi:[1,0,1]
	v_pk_fma_f32 v[82:83], v[0:1], v[70:71], v[10:11] op_sel_hi:[1,0,1]
	v_add_co_u32_e32 v0, vcc, s2, v46
	v_pk_fma_f32 v[4:5], v[2:3], v[36:37], v[4:5] op_sel_hi:[1,0,1]
	s_nop 0
	v_addc_co_u32_e32 v1, vcc, 0, v47, vcc
	v_pk_fma_f32 v[34:35], v[2:3], v[58:59], v[34:35] op_sel_hi:[1,0,1]
	v_pk_fma_f32 v[60:61], v[2:3], v[50:51], v[72:73] op_sel_hi:[1,0,1]
	v_pk_fma_f32 v[22:23], v[2:3], v[28:29], v[22:23] op_sel_hi:[1,0,1]
	v_pk_fma_f32 v[72:73], v[2:3], v[62:63], v[18:19] op_sel_hi:[1,0,1]
	v_pk_fma_f32 v[76:77], v[2:3], v[66:67], v[12:13] op_sel_hi:[1,0,1]
	v_pk_fma_f32 v[80:81], v[2:3], v[70:71], v[8:9] op_sel_hi:[1,0,1]
	global_load_dwordx4 v[0:3], v[0:1], off
	v_mov_b32_e32 v8, v37
	v_mov_b32_e32 v18, v33
	v_mov_b32_e32 v12, v51
	s_waitcnt vmcnt(0)
	v_pk_fma_f32 v[6:7], v[2:3], v[8:9], v[4:5] op_sel_hi:[1,0,1]
	v_pk_fma_f32 v[4:5], v[0:1], v[8:9], v[26:27] op_sel_hi:[1,0,1]
	v_mov_b32_e32 v8, v59
	v_mov_b32_e32 v26, v29
	v_pk_fma_f32 v[10:11], v[2:3], v[8:9], v[34:35] op_sel_hi:[1,0,1]
	v_pk_fma_f32 v[20:21], v[2:3], v[18:19], v[64:65] op_sel_hi:[1,0,1]
	v_pk_fma_f32 v[18:19], v[0:1], v[18:19], v[30:31] op_sel_hi:[1,0,1]
	v_pk_fma_f32 v[24:25], v[2:3], v[26:27], v[22:23] op_sel_hi:[1,0,1]
	v_pk_fma_f32 v[22:23], v[0:1], v[26:27], v[68:69] op_sel_hi:[1,0,1]
	v_mov_b32_e32 v26, v63
	v_mov_b32_e32 v30, v67
	v_mov_b32_e32 v34, v71
	v_pk_fma_f32 v[8:9], v[0:1], v[8:9], v[56:57] op_sel_hi:[1,0,1]
	v_pk_fma_f32 v[14:15], v[2:3], v[12:13], v[60:61] op_sel_hi:[1,0,1]
	v_pk_fma_f32 v[12:13], v[0:1], v[12:13], v[48:49] op_sel_hi:[1,0,1]
	v_pk_fma_f32 v[28:29], v[2:3], v[26:27], v[72:73] op_sel_hi:[1,0,1]
	v_pk_fma_f32 v[26:27], v[0:1], v[26:27], v[74:75] op_sel_hi:[1,0,1]
	v_pk_fma_f32 v[32:33], v[2:3], v[30:31], v[76:77] op_sel_hi:[1,0,1]
	v_pk_fma_f32 v[30:31], v[0:1], v[30:31], v[78:79] op_sel_hi:[1,0,1]
	v_pk_fma_f32 v[2:3], v[2:3], v[34:35], v[80:81] op_sel_hi:[1,0,1]
	v_pk_fma_f32 v[0:1], v[0:1], v[34:35], v[82:83] op_sel_hi:[1,0,1]
	s_cbranch_scc0 .LBB0_811
; #define LAS __attribute__((address_space(3)))
; __device__ __forceinline__ void prologue(const Params& p, LAS unsigned char* lds, int tid, int wave, int lane, int G) {
;     ...
;             for (int r = 0; r < 8; ++r) { LAS float* d = red2 + (k32 * 8 + r) * 64 + 4 * c4; d[0] = acc[r].x; d[1] = acc[r].y; d[2] = acc[r].z; d[3] = acc[r].w; }
;             __syncthreads();
;             { const int r = tid >> 6; float v = 0.f;
; #pragma unroll
;               for (int k2 = 0; k2 < 32; ++k2) v += red2[(k2 * 8 + r) * 64 + col];
;               MOD[((size_t)l * NBATCH + r) * (NMOD * DM) + n0 + col] = v + p.ada_b[(size_t)l * (NMOD * DM) + n0 + col]; }
;             __syncthreads();
	s_mul_i32 s12, s15, 0x9000
	s_mul_hi_i32 s2, s15, 0x9000
	s_add_u32 s12, s88, s12
	s_addc_u32 s2, s89, s2
	s_add_u32 s12, s12, s0
	s_addc_u32 s13, s2, s1
	ds_write_b128 v41, v[4:7] offset:32768
	ds_write_b128 v41, v[8:11] offset:33024
	ds_write_b128 v41, v[12:15] offset:33280
	ds_write_b128 v41, v[18:21] offset:33536
	ds_write_b128 v41, v[22:25] offset:33792
	ds_write_b128 v41, v[26:29] offset:34048
	ds_write_b128 v41, v[30:33] offset:34304
	ds_write_b128 v41, v[0:3] offset:34560
	s_waitcnt lgkmcnt(0)
	s_barrier
	global_load_dword v36, v16, s[12:13]
	ds_read2st64_b32 v[0:1], v52 offset0:128 offset1:136
	ds_read2st64_b32 v[2:3], v52 offset0:144 offset1:152
	ds_read2st64_b32 v[4:5], v52 offset0:160 offset1:168
	ds_read2st64_b32 v[6:7], v52 offset0:176 offset1:184
	ds_read2st64_b32 v[8:9], v52 offset0:192 offset1:200
	ds_read2st64_b32 v[10:11], v52 offset0:208 offset1:216
	ds_read2st64_b32 v[12:13], v52 offset0:224 offset1:232
	ds_read2st64_b32 v[14:15], v52 offset0:240 offset1:248
	ds_read2st64_b32 v[18:19], v53 offset0:128 offset1:136
	ds_read2st64_b32 v[20:21], v53 offset0:144 offset1:152
	ds_read2st64_b32 v[22:23], v53 offset0:160 offset1:168
	ds_read2st64_b32 v[24:25], v53 offset0:176 offset1:184
	ds_read2st64_b32 v[26:27], v53 offset0:192 offset1:200
	ds_read2st64_b32 v[28:29], v53 offset0:208 offset1:216
	ds_read2st64_b32 v[30:31], v53 offset0:224 offset1:232
	ds_read2st64_b32 v[32:33], v53 offset0:240 offset1:248
	s_waitcnt lgkmcnt(14)
	v_add_f32_e32 v0, 0, v0
	v_add_f32_e32 v0, v0, v1
	v_add_f32_e32 v0, v0, v2
	v_add_f32_e32 v0, v0, v3
	s_waitcnt lgkmcnt(13)
	v_add_f32_e32 v0, v0, v4
	v_add_f32_e32 v0, v0, v5
	s_waitcnt lgkmcnt(12)
	v_add_f32_e32 v0, v0, v6
	v_add_f32_e32 v0, v0, v7
	s_waitcnt lgkmcnt(11)
	v_add_f32_e32 v0, v0, v8
	v_add_f32_e32 v0, v0, v9
	s_waitcnt lgkmcnt(10)
	v_add_f32_e32 v0, v0, v10
	v_add_f32_e32 v0, v0, v11
	s_waitcnt lgkmcnt(9)
	v_add_f32_e32 v0, v0, v12
	v_add_f32_e32 v0, v0, v13
	s_waitcnt lgkmcnt(8)
	v_add_f32_e32 v0, v0, v14
	v_add_f32_e32 v0, v0, v15
	s_waitcnt lgkmcnt(7)
	v_add_f32_e32 v0, v0, v18
	v_add_f32_e32 v0, v0, v19
	s_waitcnt lgkmcnt(6)
	v_add_f32_e32 v0, v0, v20
	v_add_f32_e32 v0, v0, v21
	s_waitcnt lgkmcnt(5)
	v_add_f32_e32 v0, v0, v22
	v_add_f32_e32 v0, v0, v23
	s_waitcnt lgkmcnt(4)
	v_add_f32_e32 v0, v0, v24
	v_add_f32_e32 v0, v0, v25
	s_waitcnt lgkmcnt(3)
	v_add_f32_e32 v0, v0, v26
	v_add_f32_e32 v0, v0, v27
	s_waitcnt lgkmcnt(2)
	v_add_f32_e32 v0, v0, v28
	v_add_f32_e32 v0, v0, v29
	s_waitcnt lgkmcnt(1)
	v_add_f32_e32 v0, v0, v30
	v_lshl_add_u32 v37, s15, 3, v40
	v_mov_b64_e32 v[34:35], s[6:7]
	v_add_f32_e32 v0, v0, v31
	v_mad_i64_i32 v[34:35], s[12:13], v37, s97, v[34:35]
	s_waitcnt lgkmcnt(0)
	v_add_f32_e32 v0, v0, v32
	v_lshl_add_u64 v[34:35], v[34:35], 0, s[0:1]
	s_add_i32 s14, s14, s10
	v_add_f32_e32 v0, v0, v33
	v_lshl_add_u64 v[34:35], v[34:35], 0, v[16:17]
	s_cmpk_gt_i32 s14, 0x23f
	s_waitcnt vmcnt(0)
	v_add_f32_e32 v0, v0, v36
	global_store_dword v[34:35], v0, off
	s_barrier
	s_cbranch_scc0 .LBB0_810
